# kernel-start grid sync: only workgroup 0 (the one that wrote) issues the L2 write-back
# baseline (speedup 1.0000x reference)
; __global__ void __launch_bounds__(512) fwd_kernel(Args a) {
;     ...
;     if (a.ph_lo == 0) { if (blockIdx.x == 0) for (int i = tid; i < XCD_BAR_WORDS; i += 512) ((unsigned*)(a.ws + WS_BAR))[i] = 0u;
;         grid.sync(); (void)xcd_barrier_post((unsigned*)(a.ws + WS_BAR), xst); }
.LBB0_11:
	v_lshrrev_b32_e32 v1, 20, v0
	v_lshrrev_b32_e32 v0, 10, v0
	v_or_b32_e32 v0, v0, v1
	s_movk_i32 s3, 0x3ff
	v_and_or_b32 v0, v0, s3, v178
	v_cmp_eq_u32_e32 vcc, 0, v0
	s_barrier
	s_and_saveexec_b64 s[4:5], vcc
	s_cbranch_execz .LBB0_21
	s_cmp_lg_u32 s2, 0
	s_cbranch_scc1 .Lstart_nowb
	buffer_wbl2 sc1
.Lstart_nowb:
	s_waitcnt vmcnt(0)
	s_load_dwordx2 s[6:7], s[6:7], 0x58
	v_mov_b32_e32 v2, 0
	s_mov_b64 s[8:9], exec
	v_mbcnt_lo_u32_b32 v1, s8, 0
	v_mbcnt_hi_u32_b32 v1, s9, v1
	s_waitcnt lgkmcnt(0)
	global_load_dword v0, v2, s[6:7] offset:40
	v_cmp_eq_u32_e32 vcc, 0, v1
	s_and_saveexec_b64 s[10:11], vcc
	s_cbranch_execz .LBB0_14
	s_bcnt1_i32_b64 s3, s[8:9]
	v_mov_b32_e32 v3, s3
	global_atomic_add v3, v2, v3, s[6:7] offset:32 sc0
